# P5 LayerNorm: gamma/beta loaded once before the row loop into spare registers; the 4 serialized per-row-pair gamma/beta load + vmcnt(0) steps (which also drained the row's stores) become register copi
# speedup vs baseline: 1.0312x; 1.0010x over previous
; __device__ __forceinline__ int opaque_tid() { int t = threadIdx.x; asm volatile("" : "+v"(t)); return t; }
; __device__ __forceinline__ void ln_row2(const float* x0, const float* x1, const float* g, const float* b, float* o0, float* o1, bf16_t* ob0, bf16_t* ob1, int lane, float* st0, float* st1, bool wx) {
;     ...
;     for (int j = 0; j < 4; ++j) { const f32x4 gg = ((const f32x4*)g)[lane + 64 * j], bb = ((const f32x4*)b)[lane + 64 * j];
;         const f32x4 y0 = v[j] * rstd0 * gg + bb, y1 = w[j] * rstd1 * gg + bb;
; __global__ void __launch_bounds__(NWAVES * 64, 2) mega_fwd(Args args) {
;     ...
;             { const int lane5 = opaque_tid() & 63;
;               for (int m = row0g + gw; m < row0g + CH; m += 2 * NGW) {
;                 const int m1 = m + NGW;
;                 if (m1 < row0g + CH) ln_row2(X + (size_t)m * DM, X + (size_t)m1 * DM, args.in[19] + L * DM, args.in[20] + L * DM, X + (size_t)m * DM, X + (size_t)m1 * DM, xb + (size_t)m * DM, xb + (size_t)m1 * DM, lane5, rstat + 2 * (size_t)m, rstat + 2 * (size_t)m1, L == DEPTH - 1);
;                 else ln_row(X + (size_t)m * DM, args.in[19] + L * DM, args.in[20] + L * DM, X + (size_t)m * DM, xb + (size_t)m * DM, lane5, rstat + 2 * (size_t)m, L == DEPTH - 1); } }
.LBB0_862:
	s_or_b64 exec, exec, s[0:1]
	v_readlane_b32 s0, v249, 27
	v_readlane_b32 s1, v249, 28
	s_waitcnt lgkmcnt(0)
	v_mov_b32_e32 v0, v180
	s_andn2_b64 vcc, exec, s[0:1]
	s_barrier
	s_cbranch_vccnz .LBB0_152
	v_readlane_b32 s0, v249, 26
	s_add_i32 s4, s24, s0
	v_readlane_b32 s0, v251, 51
	v_readlane_b32 s1, v251, 52
	s_add_i32 s40, s24, s0
	v_and_b32_e32 v32, 63, v0
	v_readlane_b32 s0, v249, 61
	v_lshlrev_b32_e32 v96, 4, v32
	v_readlane_b32 s1, v249, 62
	v_lshlrev_b32_e32 v0, 3, v32
	v_mov_b32_e32 v1, v97
	v_lshl_add_u64 v[34:35], s[0:1], 0, v[96:97]
	v_readlane_b32 s0, v249, 63
	v_readlane_b32 s1, v248, 0
	v_lshl_add_u64 v[40:41], s[94:95], 0, v[96:97]
	v_cmp_eq_u32_e64 s[36:37], 0, v32
	v_lshl_add_u64 v[36:37], s[0:1], 0, v[96:97]
	v_readlane_b32 s0, v251, 53
	v_readlane_b32 s1, v251, 54
	v_or_b32_e32 v96, 0x600, v0
	s_nop 0
	v_lshl_add_u64 v[38:39], s[0:1], 0, v[0:1]
	v_lshl_add_u64 v[42:43], s[0:1], 0, v[96:97]
	global_load_dwordx4 v[80:83], v[34:35], off
	global_load_dwordx4 v[98:101], v[36:37], off
	global_load_dwordx4 v[84:87], v[34:35], off offset:1024
	global_load_dwordx4 v[102:105], v[36:37], off offset:1024
	global_load_dwordx4 v[88:91], v[34:35], off offset:2048
	global_load_dwordx4 v[106:109], v[36:37], off offset:2048
	global_load_dwordx4 v[92:95], v[34:35], off offset:3072
	global_load_dwordx4 v[110:113], v[36:37], off offset:3072
	s_branch .LBB0_866

; __device__ __forceinline__ unsigned cvt_pk_bf16(float lo, float hi) { unsigned r; asm volatile("v_cvt_pk_bf16_f32 %0, %1, %2" : "=v"(r) : "v"(lo), "v"(hi)); return r; }
; __device__ __forceinline__ void ln_row(const float* xrow, const float* g, const float* b, float* orow, bf16_t* obrow, int lane, float* st, bool wx) {
;     ...
; #pragma unroll
;     for (int j = 0; j < 4; ++j) { const f32x4 gg = ((const f32x4*)g)[lane + 64 * j], bb = ((const f32x4*)b)[lane + 64 * j];
;         const f32x4 y = v[j] * rstd * gg + bb;
;         if (wx) ((f32x4*)orow)[lane + 64 * j] = y;
;         u32x2 w; w.x = cvt_pk_bf16(y.x, y.y); w.y = cvt_pk_bf16(y.z, y.w);
;         ((u32x2*)obrow)[lane + 64 * j] = w; }
.LBB0_869:
	s_or_b64 exec, exec, s[0:1]
	v_pk_mul_f32 v[2:3], v[18:19], v[20:21] op_sel_hi:[1,0]
	v_pk_mul_f32 v[10:11], v[12:13], v[20:21] op_sel_hi:[1,0]
	v_cndmask_b32_e64 v12, 0, 1, s[26:27]
	v_lshl_add_u64 v[22:23], s[42:43], 0, v[96:97]
	v_cmp_ne_u32_e64 s[38:39], 1, v12
	s_andn2_b64 vcc, exec, s[26:27]
	v_mov_b32_e32 v24, v80
	v_mov_b32_e32 v25, v81
	v_mov_b32_e32 v26, v82
	v_mov_b32_e32 v27, v83
	v_mov_b32_e32 v28, v98
	v_mov_b32_e32 v29, v99
	v_mov_b32_e32 v30, v100
	v_mov_b32_e32 v31, v101
	v_pk_fma_f32 v[12:13], v[2:3], v[26:27], v[30:31]
	v_pk_fma_f32 v[10:11], v[10:11], v[24:25], v[28:29]
	s_cbranch_vccnz .LBB0_871
	global_store_dwordx4 v[22:23], v[10:13], off
.LBB0_871:
	v_cvt_pk_bf16_f32 v2, v10, v11
	s_nop 1
	v_lshl_add_u64 v[10:11], s[34:35], 1, v[38:39]
	v_cvt_pk_bf16_f32 v3, v12, v13
	global_store_dwordx2 v[10:11], v[2:3], off
	v_mov_b32_e32 v21, v20
	v_mov_b32_e32 v12, v20
	v_mov_b32_e32 v13, v20
	v_pk_mul_f32 v[2:3], v[14:15], v[12:13]
	v_pk_mul_f32 v[14:15], v[4:5], v[20:21]
	s_and_b64 vcc, exec, s[38:39]
	v_mov_b32_e32 v24, v84
	v_mov_b32_e32 v25, v85
	v_mov_b32_e32 v26, v86
	v_mov_b32_e32 v27, v87
	v_mov_b32_e32 v28, v102
	v_mov_b32_e32 v29, v103
	v_mov_b32_e32 v30, v104
	v_mov_b32_e32 v31, v105
	v_pk_fma_f32 v[4:5], v[2:3], v[26:27], v[30:31]
	v_pk_fma_f32 v[2:3], v[14:15], v[24:25], v[28:29]
	s_cbranch_vccnz .LBB0_873
	global_store_dwordx4 v[22:23], v[2:5], off offset:1024
.LBB0_873:
	s_nop 1
	v_cvt_pk_bf16_f32 v2, v2, v3
	v_cvt_pk_bf16_f32 v3, v4, v5
	global_store_dwordx2 v[10:11], v[2:3], off offset:512
	s_nop 0
	v_pk_mul_f32 v[12:13], v[16:17], v[12:13]
	v_pk_mul_f32 v[8:9], v[8:9], v[20:21]
	s_and_b64 vcc, exec, s[38:39]
	v_mov_b32_e32 v2, v88
	v_mov_b32_e32 v3, v89
	v_mov_b32_e32 v4, v90
	v_mov_b32_e32 v5, v91
	v_mov_b32_e32 v24, v106
	v_mov_b32_e32 v25, v107
	v_mov_b32_e32 v26, v108
	v_mov_b32_e32 v27, v109
	v_pk_fma_f32 v[4:5], v[12:13], v[4:5], v[26:27]
	v_pk_fma_f32 v[2:3], v[8:9], v[2:3], v[24:25]
	s_cbranch_vccnz .LBB0_875
	global_store_dwordx4 v[22:23], v[2:5], off offset:2048
.LBB0_875:
	s_nop 1
	v_cvt_pk_bf16_f32 v2, v2, v3
	v_cvt_pk_bf16_f32 v3, v4, v5
	global_store_dwordx2 v[10:11], v[2:3], off offset:1024
	s_nop 0
	v_mov_b32_e32 v2, v20
	v_mov_b32_e32 v3, v20
	v_pk_mul_f32 v[0:1], v[0:1], v[20:21]
	v_pk_mul_f32 v[2:3], v[6:7], v[2:3]
	s_and_b64 vcc, exec, s[38:39]
	v_mov_b32_e32 v8, v92
	v_mov_b32_e32 v9, v93
	v_mov_b32_e32 v10, v94
	v_mov_b32_e32 v11, v95
	v_mov_b32_e32 v12, v110
	v_mov_b32_e32 v13, v111
	v_mov_b32_e32 v14, v112
	v_mov_b32_e32 v15, v113
	v_pk_fma_f32 v[2:3], v[2:3], v[10:11], v[14:15]
	v_pk_fma_f32 v[0:1], v[0:1], v[8:9], v[12:13]
	s_cbranch_vccnz .LBB0_877
	global_store_dwordx4 v[22:23], v[0:3], off offset:3072

; __device__ __forceinline__ unsigned cvt_pk_bf16(float lo, float hi) { unsigned r; asm volatile("v_cvt_pk_bf16_f32 %0, %1, %2" : "=v"(r) : "v"(lo), "v"(hi)); return r; }
; __device__ __forceinline__ void ln_row2(const float* x0, const float* x1, const float* g, const float* b, float* o0, float* o1, bf16_t* ob0, bf16_t* ob1, int lane, float* st0, float* st1, bool wx) {
;     ...
; #pragma unroll
;     for (int j = 0; j < 4; ++j) { const f32x4 gg = ((const f32x4*)g)[lane + 64 * j], bb = ((const f32x4*)b)[lane + 64 * j];
;         const f32x4 y0 = v[j] * rstd0 * gg + bb, y1 = w[j] * rstd1 * gg + bb;
;         if (wx) { ((f32x4*)o0)[lane + 64 * j] = y0; ((f32x4*)o1)[lane + 64 * j] = y1; }
;         u32x2 p0; p0.x = cvt_pk_bf16(y0.x, y0.y); p0.y = cvt_pk_bf16(y0.z, y0.w); ((u32x2*)ob0)[lane + 64 * j] = p0;
;         u32x2 p1; p1.x = cvt_pk_bf16(y1.x, y1.y); p1.y = cvt_pk_bf16(y1.z, y1.w); ((u32x2*)ob1)[lane + 64 * j] = p1; }
.LBB0_881:
	s_or_b64 exec, exec, s[0:1]
	v_pk_mul_f32 v[6:7], v[50:51], v[54:55] op_sel_hi:[1,0]
	v_pk_mul_f32 v[14:15], v[28:29], v[54:55] op_sel_hi:[1,0]
	v_pk_mul_f32 v[18:19], v[26:27], v[56:57] op_sel_hi:[1,0]
	v_pk_mul_f32 v[22:23], v[24:25], v[56:57] op_sel_hi:[1,0]
	v_cndmask_b32_e64 v24, 0, 1, s[26:27]
	v_lshl_add_u64 v[58:59], s[42:43], 0, v[96:97]
	v_cmp_ne_u32_e64 s[38:39], 1, v24
	s_andn2_b64 vcc, exec, s[26:27]
	v_mov_b32_e32 v60, v80
	v_mov_b32_e32 v61, v81
	v_mov_b32_e32 v62, v82
	v_mov_b32_e32 v63, v83
	v_mov_b32_e32 v64, v98
	v_mov_b32_e32 v65, v99
	v_mov_b32_e32 v66, v100
	v_mov_b32_e32 v67, v101
	v_pk_fma_f32 v[28:29], v[6:7], v[62:63], v[66:67]
	v_pk_fma_f32 v[26:27], v[14:15], v[60:61], v[64:65]
	v_pk_fma_f32 v[24:25], v[18:19], v[62:63], v[66:67]
	v_pk_fma_f32 v[22:23], v[22:23], v[60:61], v[64:65]
	s_cbranch_vccnz .LBB0_883
	global_store_dwordx4 v[58:59], v[26:29], off
	global_store_dwordx4 v[44:45], v[22:25], off
.LBB0_883:
	s_lshl_b64 s[0:1], s[24:25], 10
	v_cvt_pk_bf16_f32 v6, v26, v27
	v_lshl_add_u64 v[26:27], s[34:35], 1, v[38:39]
	v_cvt_pk_bf16_f32 v7, v28, v29
	global_store_dwordx2 v[26:27], v[6:7], off
	v_cvt_pk_bf16_f32 v6, v22, v23
	v_lshl_add_u64 v[22:23], s[0:1], 1, v[38:39]
	v_cvt_pk_bf16_f32 v7, v24, v25
	global_store_dwordx2 v[22:23], v[6:7], off
	v_mov_b32_e32 v6, v54
	v_mov_b32_e32 v7, v54
	v_mov_b32_e32 v55, v54
	v_mov_b32_e32 v57, v56
	v_pk_mul_f32 v[14:15], v[48:49], v[6:7]
	v_mov_b32_e32 v24, v56
	v_mov_b32_e32 v25, v56
	v_pk_mul_f32 v[18:19], v[20:21], v[54:55]
	v_pk_mul_f32 v[28:29], v[16:17], v[56:57]
	s_and_b64 vcc, exec, s[38:39]
	v_mov_b32_e32 v60, v84
	v_mov_b32_e32 v61, v85
	v_mov_b32_e32 v62, v86
	v_mov_b32_e32 v63, v87
	v_mov_b32_e32 v64, v102
	v_mov_b32_e32 v65, v103
	v_mov_b32_e32 v66, v104
	v_mov_b32_e32 v67, v105
	v_pk_fma_f32 v[20:21], v[14:15], v[62:63], v[66:67]
	v_pk_mul_f32 v[14:15], v[52:53], v[24:25]
	v_pk_fma_f32 v[18:19], v[18:19], v[60:61], v[64:65]
	v_pk_fma_f32 v[16:17], v[14:15], v[62:63], v[66:67]
	v_pk_fma_f32 v[14:15], v[28:29], v[60:61], v[64:65]
	s_cbranch_vccnz .LBB0_885
	global_store_dwordx4 v[58:59], v[18:21], off offset:1024
	global_store_dwordx4 v[44:45], v[14:17], off offset:1024
.LBB0_885:
	s_nop 0
	v_cvt_pk_bf16_f32 v18, v18, v19
	v_cvt_pk_bf16_f32 v19, v20, v21
	global_store_dwordx2 v[26:27], v[18:19], off offset:512
	v_cvt_pk_bf16_f32 v14, v14, v15
	v_cvt_pk_bf16_f32 v15, v16, v17
	global_store_dwordx2 v[22:23], v[14:15], off offset:512
	s_nop 0
	v_pk_mul_f32 v[6:7], v[46:47], v[6:7]
	v_pk_mul_f32 v[28:29], v[12:13], v[54:55]
	v_pk_mul_f32 v[24:25], v[10:11], v[24:25]
	v_pk_mul_f32 v[46:47], v[8:9], v[56:57]
	s_and_b64 vcc, exec, s[38:39]
	v_mov_b32_e32 v14, v88
	v_mov_b32_e32 v15, v89
	v_mov_b32_e32 v16, v90
	v_mov_b32_e32 v17, v91
	v_mov_b32_e32 v18, v106
	v_mov_b32_e32 v19, v107
	v_mov_b32_e32 v20, v108
	v_mov_b32_e32 v21, v109
	v_pk_fma_f32 v[12:13], v[6:7], v[16:17], v[20:21]
	v_pk_fma_f32 v[10:11], v[28:29], v[14:15], v[18:19]
	v_pk_fma_f32 v[8:9], v[24:25], v[16:17], v[20:21]
	v_pk_fma_f32 v[6:7], v[46:47], v[14:15], v[18:19]
	s_cbranch_vccnz .LBB0_887
	global_store_dwordx4 v[58:59], v[10:13], off offset:2048
	global_store_dwordx4 v[44:45], v[6:9], off offset:2048
.LBB0_887:
	s_nop 0
	v_cvt_pk_bf16_f32 v10, v10, v11
	v_cvt_pk_bf16_f32 v11, v12, v13
	global_store_dwordx2 v[26:27], v[10:11], off offset:1024
	v_cvt_pk_bf16_f32 v6, v6, v7
	v_cvt_pk_bf16_f32 v7, v8, v9
	global_store_dwordx2 v[22:23], v[6:7], off offset:1024
	v_mov_b32_e32 v6, v54
	v_mov_b32_e32 v7, v54
	v_mov_b32_e32 v16, v56
	v_mov_b32_e32 v17, v56
	v_pk_mul_f32 v[0:1], v[0:1], v[54:55]
	v_pk_mul_f32 v[18:19], v[4:5], v[56:57]
	v_pk_mul_f32 v[2:3], v[2:3], v[6:7]
	v_pk_mul_f32 v[16:17], v[30:31], v[16:17]
	s_and_b64 vcc, exec, s[38:39]
	v_mov_b32_e32 v8, v92
	v_mov_b32_e32 v9, v93
	v_mov_b32_e32 v10, v94
	v_mov_b32_e32 v11, v95
	v_mov_b32_e32 v12, v110
	v_mov_b32_e32 v13, v111
	v_mov_b32_e32 v14, v112
	v_mov_b32_e32 v15, v113
	v_pk_fma_f32 v[6:7], v[2:3], v[10:11], v[14:15]
	v_pk_fma_f32 v[4:5], v[0:1], v[8:9], v[12:13]
	v_pk_fma_f32 v[2:3], v[16:17], v[10:11], v[14:15]
	v_pk_fma_f32 v[0:1], v[18:19], v[8:9], v[12:13]
	s_cbranch_vccnz .LBB0_889
	global_store_dwordx4 v[58:59], v[4:7], off offset:3072
	global_store_dwordx4 v[44:45], v[0:3], off offset:3072
